# seam 7 replaced by per-panel data-flow waits (attention O write-through + per-panel arrival words, GLU tiles, conversion-done and Y-done words)
# speedup vs baseline: 1.0311x; 1.0018x over previous
; __device__ __forceinline__ int crow(int r,int hi){return (r&3)+8*(r>>2)+4*hi;}
; template<int THRL> __device__ __forceinline__ void attn_unit(int b,int h,int qb,const bf16*Q,const bf16*__restrict__ K,const bf16*__restrict__ V,bf16*O,char*shm,float m2){
;     ...
;   if(hi==0)wsf[32+r32]=l_reg;asm volatile("s_waitcnt lgkmcnt(0)":::"memory");
;   float rli[16];
;   #pragma unroll
;   for(int r=0;r<16;++r)rli[r]=__builtin_amdgcn_rcpf(wsf[32+crow(r,hi)]);
;   bf16*Ow=O+(rowbase+q0+wid*QBLK)*QP+h*D;
;   { bf16*stg=(bf16*)(shm+LDS_OST)+wid*2048;
;     #pragma unroll
;     for(int r=0;r<16;++r){const int orow=crow(r,hi);
;       #pragma unroll
;       for(int d0=0;d0<2;++d0)stg[orow*64+d0*32+r32]=__float2bfloat16(o[d0][r]*rli[r]);}
;     asm volatile("s_waitcnt lgkmcnt(0)":::"memory");
;     #pragma unroll
;     for(int i=0;i<4;++i){const int row=i*8+(lane>>3),ch=lane&7; const u32x4 v=*(const u32x4*)(stg+row*64+ch*8); ATTN_STORE16(Ow+(long)row*QP+ch*8,v);} }
;   __builtin_amdgcn_s_setprio(0);
;   asm volatile("s_waitcnt lgkmcnt(0)\n\ts_barrier":::"memory");
.LBB0_823:
	s_or_b64 exec, exec, s[4:5]
	s_waitcnt lgkmcnt(0)
	v_add_u32_e32 v58, s0, v222
	ds_read_b128 v[50:53], v58 offset:49280
	ds_read_b128 v[54:57], v58 offset:49312
	s_lshl_b32 s0, s9, 12
	s_add_i32 s0, s0, 0
	v_mov_b32_e32 v201, v191
	s_waitcnt lgkmcnt(1)
	v_rcp_f32_e32 v59, v50
	v_rcp_f32_e32 v60, v51
	v_rcp_f32_e32 v61, v52
	v_rcp_f32_e32 v62, v53
	s_waitcnt lgkmcnt(0)
	v_rcp_f32_e32 v63, v54
	ds_read_b128 v[50:53], v58 offset:49344
	v_rcp_f32_e32 v64, v55
	v_rcp_f32_e32 v65, v56
	v_rcp_f32_e32 v66, v57
	ds_read_b128 v[54:57], v58 offset:49376
	v_lshlrev_b32_e32 v58, 1, v1
	v_mul_f32_e32 v18, v18, v59
	v_add3_u32 v58, s0, v223, v58
	v_cvt_pk_bf16_f32 v18, v18, s0
	ds_write_b16 v58, v18 offset:51200
	v_mul_f32_e32 v18, v34, v59
	v_cvt_pk_bf16_f32 v18, v18, s0
	ds_write_b16 v58, v18 offset:51264
	v_mul_f32_e32 v18, v19, v60
	v_cvt_pk_bf16_f32 v18, v18, s0
	ds_write_b16 v58, v18 offset:51328
	v_mul_f32_e32 v18, v35, v60
	v_cvt_pk_bf16_f32 v18, v18, s0
	ds_write_b16 v58, v18 offset:51392
	v_mul_f32_e32 v18, v20, v61
	v_cvt_pk_bf16_f32 v18, v18, s0
	ds_write_b16 v58, v18 offset:51456
	v_mul_f32_e32 v18, v36, v61
	v_cvt_pk_bf16_f32 v18, v18, s0
	ds_write_b16 v58, v18 offset:51520
	v_mul_f32_e32 v18, v21, v62
	v_cvt_pk_bf16_f32 v18, v18, s0
	ds_write_b16 v58, v18 offset:51584
	v_mul_f32_e32 v18, v37, v62
	v_cvt_pk_bf16_f32 v18, v18, s0
	ds_write_b16 v58, v18 offset:51648
	v_mul_f32_e32 v18, v22, v63
	v_cvt_pk_bf16_f32 v18, v18, s0
	ds_write_b16 v58, v18 offset:52224
	v_mul_f32_e32 v18, v38, v63
	v_cvt_pk_bf16_f32 v18, v18, s0
	ds_write_b16 v58, v18 offset:52288
	v_mul_f32_e32 v18, v23, v64
	v_cvt_pk_bf16_f32 v18, v18, s0
	ds_write_b16 v58, v18 offset:52352
	v_mul_f32_e32 v18, v39, v64
	v_cvt_pk_bf16_f32 v18, v18, s0
	ds_write_b16 v58, v18 offset:52416
	v_mul_f32_e32 v18, v24, v65
	v_cvt_pk_bf16_f32 v18, v18, s0
	ds_write_b16 v58, v18 offset:52480
	v_mul_f32_e32 v18, v40, v65
	v_cvt_pk_bf16_f32 v18, v18, s0
	s_waitcnt lgkmcnt(14)
	v_rcp_f32_e32 v50, v50
	ds_write_b16 v58, v18 offset:52544
	v_mul_f32_e32 v18, v25, v66
	v_cvt_pk_bf16_f32 v18, v18, s0
	ds_write_b16 v58, v18 offset:52608
	v_mul_f32_e32 v18, v41, v66
	v_cvt_pk_bf16_f32 v18, v18, s0
	v_rcp_f32_e32 v51, v51
	ds_write_b16 v58, v18 offset:52672
	v_mul_f32_e32 v18, v26, v50
	v_cvt_pk_bf16_f32 v18, v18, s0
	ds_write_b16 v58, v18 offset:53248
	v_mul_f32_e32 v18, v42, v50
	v_cvt_pk_bf16_f32 v18, v18, s0
	v_rcp_f32_e32 v52, v52
	ds_write_b16 v58, v18 offset:53312
	v_mul_f32_e32 v18, v27, v51
	v_cvt_pk_bf16_f32 v18, v18, s0
	ds_write_b16 v58, v18 offset:53376
	v_mul_f32_e32 v18, v43, v51
	v_cvt_pk_bf16_f32 v18, v18, s0
	v_rcp_f32_e32 v53, v53
	ds_write_b16 v58, v18 offset:53440
	v_mul_f32_e32 v18, v28, v52
	v_cvt_pk_bf16_f32 v18, v18, s0
	ds_write_b16 v58, v18 offset:53504
	v_mul_f32_e32 v18, v44, v52
	v_cvt_pk_bf16_f32 v18, v18, s0
	s_waitcnt lgkmcnt(14)
	v_rcp_f32_e32 v54, v54
	ds_write_b16 v58, v18 offset:53568
	v_mul_f32_e32 v18, v29, v53
	v_cvt_pk_bf16_f32 v18, v18, s0
	ds_write_b16 v58, v18 offset:53632
	v_mul_f32_e32 v18, v45, v53
	v_cvt_pk_bf16_f32 v18, v18, s0
	v_rcp_f32_e32 v55, v55
	ds_write_b16 v58, v18 offset:53696
	v_mul_f32_e32 v18, v30, v54
	v_cvt_pk_bf16_f32 v18, v18, s0
	ds_write_b16 v58, v18 offset:54272
	v_mul_f32_e32 v18, v46, v54
	v_cvt_pk_bf16_f32 v18, v18, s0
	v_rcp_f32_e32 v56, v56
	ds_write_b16 v58, v18 offset:54336
	v_mul_f32_e32 v18, v31, v55
	v_cvt_pk_bf16_f32 v18, v18, s0
	ds_write_b16 v58, v18 offset:54400
	v_mul_f32_e32 v18, v47, v55
	v_cvt_pk_bf16_f32 v18, v18, s0
	v_rcp_f32_e32 v57, v57
	ds_write_b16 v58, v18 offset:54464
	v_mul_f32_e32 v18, v32, v56
	v_cvt_pk_bf16_f32 v18, v18, s0
	ds_write_b16 v58, v18 offset:54528
	v_mul_f32_e32 v18, v48, v56
	v_cvt_pk_bf16_f32 v18, v18, s0
	ds_write_b16 v58, v18 offset:54592
	v_mul_f32_e32 v18, v33, v57
	v_cvt_pk_bf16_f32 v18, v18, s0
	ds_write_b16 v58, v18 offset:54656
	v_mul_f32_e32 v18, v49, v57
	v_cvt_pk_bf16_f32 v18, v18, s0
	ds_write_b16 v58, v18 offset:54720
	v_add_u32_e32 v30, s0, v200
	s_waitcnt lgkmcnt(0)
	v_add_u32_e32 v18, v30, v224
	ds_read_b128 v[18:21], v18 offset:51200
	v_add_u32_e32 v22, v30, v225
	ds_read_b128 v[22:25], v22 offset:51200
	v_lshl_add_u64 v[26:27], s[54:55], 0, v[200:201]
	v_mov_b32_e32 v203, v191
	v_lshl_add_u64 v[28:29], v[26:27], 0, v[202:203]
	v_mov_b32_e32 v205, v191
	s_waitcnt lgkmcnt(1)
	global_store_dwordx4 v[28:29], v[18:21], off sc1
	v_mov_b32_e32 v207, v191
	v_lshl_add_u64 v[28:29], v[26:27], 0, v[206:207]
	v_lshl_add_u64 v[18:19], v[26:27], 0, v[204:205]
	s_waitcnt lgkmcnt(0)
	global_store_dwordx4 v[18:19], v[22:25], off sc1
	v_add_u32_e32 v18, v30, v226
	ds_read_b128 v[18:21], v18 offset:51200
	v_add_u32_e32 v22, v30, v227
	ds_read_b128 v[22:25], v22 offset:51200
	v_mov_b32_e32 v209, v191
	s_waitcnt lgkmcnt(1)
	global_store_dwordx4 v[28:29], v[18:21], off sc1
	s_nop 1
	v_lshl_add_u64 v[18:19], v[26:27], 0, v[208:209]
	s_waitcnt lgkmcnt(0)
	global_store_dwordx4 v[18:19], v[22:25], off sc1
	s_setprio 0
	s_waitcnt lgkmcnt(0)
	s_barrier

; #define LAS __attribute__((address_space(3)))
; #define OPAQUE_TID() int tid = threadIdx.x; asm volatile("" : "+v"(tid)); const int lane = tid & 63; const int wave = __builtin_amdgcn_readfirstlane(tid >> 6); (void)lane; (void)wave
; __global__ void __launch_bounds__(NWAVES * 64, 2) mega_fwd(Args args) {
;     ...
;         asm volatile("s_waitcnt vmcnt(0) lgkmcnt(0)" ::: "memory"); __syncthreads();
;         if (bx >= 64 && bx < 128) {
;             OPAQUE_TID(); LAS float* scr = (LAS float*)(lds + wave * 16384);
;             constexpr int J_GU = (DM / 64) * (FF / 64), J_D = (FF / 64) * (DM / 64), J_GLU = (512 / 64) * (512 / 64), J_BR = (512 / 64) * (DM / 64), J_SQ = (DM / 64) * (DM / 64), J_PP = (PLE / 64) * (DM / 64);
;             for (int it = (bx - 64) * NWAVES + wave; it < 2 * J_GU + J_D + J_GLU + 2 * J_BR + 2 * J_SQ + J_PP; it += 64 * NWAVES) { int r = it;
;                 if (r < J_GLU) { p0_transpose_item(args.in[18], 512, 512, Wglu, nullptr, 0, scr, r, lane); continue; } r -= J_GLU;
;                 if (r < J_BR) { p0_transpose_item(args.in[20], 512, DM, Wab, nullptr, 0, scr, r, lane); continue; } r -= J_BR;
;                 if (r < J_BR) { p0_transpose_item(args.in[21], 512, DM, Wsb, nullptr, 0, scr, r, lane); continue; } r -= J_BR;
;                 if (r < J_SQ) { p0_transpose_item(args.in[22], DM, DM, Wout, nullptr, 0, scr, r, lane); continue; } r -= J_SQ;
;                 if (r < J_GU) { p0_transpose_item(args.in[24], DM, FF, W2gu, args.in[23], 1, scr, r, lane); continue; } r -= J_GU;
;                 if (r < J_GU) { p0_transpose_item(args.in[25], DM, FF, W2gu, args.in[23], 2, scr, r, lane); continue; } r -= J_GU;
;                 if (r < J_D) { p0_transpose_item(args.in[26], FF, DM, W2d, nullptr, 0, scr, r, lane); continue; } r -= J_D;
;                 if (r < J_SQ) { p0_transpose_item(args.in[28], DM, DM, Wpg, args.in[27], 0, scr, r, lane); continue; } r -= J_SQ;
;                 p0_transpose_item(args.in[29], PLE, DM, Wpp, nullptr, 0, scr, r, lane); }
.LBB0_832:
	s_waitcnt vmcnt(0) lgkmcnt(0)
	s_barrier
	s_and_saveexec_b64 s[0:1], s[74:75]
	s_cbranch_execz .Latt_arr_done
	s_bfe_u32 s2, s88, 0x10002
	s_lshl_b32 s2, s2, 5
	s_bfe_u32 s3, s88, 0x40003
	s_lshl_b32 s3, s3, 1
	s_add_i32 s2, s2, s3
	s_lshl_b32 s2, s2, 6
	s_add_i32 s2, s2, 0x9000
	v_readlane_b32 s4, v252, 26
	v_readlane_b32 s5, v252, 27
	v_mov_b32_e32 v1, s2
	v_mov_b32_e32 v2, 1
	s_nop 4
	global_atomic_add v1, v2, s[4:5]
	global_atomic_add v1, v2, s[4:5] offset:64
.Latt_arr_done:
	s_or_b64 exec, exec, s[0:1]
	s_and_b32 s0, s88, 0xffffffc0
	v_readlane_b32 s52, v251, 40
	v_readlane_b32 s8, v251, 24
	s_cmp_eq_u32 s0, 64
	v_readlane_b32 s53, v251, 41
	v_readlane_b32 s54, v251, 42
	v_readlane_b32 s55, v251, 43
	v_readlane_b32 s56, v251, 44
	v_readlane_b32 s57, v251, 45
	v_readlane_b32 s58, v251, 46
	v_readlane_b32 s59, v251, 47
	v_readlane_b32 s60, v251, 48
	v_readlane_b32 s61, v251, 49
	v_readlane_b32 s62, v251, 50
	v_readlane_b32 s63, v251, 51
	v_readlane_b32 s64, v251, 52
	v_readlane_b32 s65, v251, 53
	v_readlane_b32 s66, v251, 54
	v_readlane_b32 s67, v251, 55
	v_readlane_b32 s12, v251, 28
	v_readlane_b32 s13, v251, 29
	v_readlane_b32 s16, v251, 32
	v_readlane_b32 s17, v251, 33
	v_readlane_b32 s18, v251, 34
	v_readlane_b32 s19, v251, 35
	v_readlane_b32 s20, v251, 36
	v_readlane_b32 s21, v251, 37
	v_readlane_b32 s22, v251, 38
	v_readlane_b32 s23, v251, 39
	s_barrier
	v_readlane_b32 s9, v251, 25
	v_readlane_b32 s10, v251, 26
	v_readlane_b32 s11, v251, 27
	v_readlane_b32 s14, v251, 30
	v_readlane_b32 s15, v251, 31
	s_cbranch_scc0 .LBB0_917
	v_mov_b32_e32 v2, v0
	s_lshl_b32 s1, s88, 3
	v_readfirstlane_b32 s0, v2
	s_ashr_i32 s0, s0, 6
	s_add_i32 s1, s1, s0
	s_add_i32 s4, s1, 0xfffffe00
	s_cmpk_gt_i32 s4, 0xbbf
	s_cbranch_scc1 .LBB0_916
	s_lshl_b32 s0, s0, 14
	v_bfe_u32 v1, v2, 3, 3
	v_lshlrev_b32_e32 v3, 4, v2
	v_lshlrev_b32_e32 v2, 3, v2
	s_add_i32 s0, s0, 0
	v_and_b32_e32 v66, 0x70, v3
	v_and_b32_e32 v2, 56, v2
	v_add_u32_e32 v4, s0, v66
	s_movk_i32 s1, 0x84
	v_mul_u32_u24_e32 v5, 0x84, v2
	v_mov_b32_e32 v6, 0x420
	v_lshlrev_b32_e32 v7, 2, v1
	v_mov_b32_e32 v67, 0
	v_mad_u32_u24 v103, v1, s1, v4
	v_mad_u32_u24 v6, v1, s1, v6
	v_add3_u32 v111, s0, v5, v7
	v_readlane_b32 s0, v252, 18
	v_lshlrev_b32_e32 v2, 1, v2
	v_mov_b32_e32 v3, v67
	v_readlane_b32 s1, v252, 19
	v_readlane_b32 s6, v252, 12
	s_cmp_lg_u64 s[58:59], 0
	v_lshl_add_u64 v[74:75], s[0:1], 0, v[2:3]
	v_readlane_b32 s0, v252, 22
	v_readlane_b32 s1, v252, 23
	v_readlane_b32 s7, v252, 13
	s_cselect_b64 s[10:11], -1, 0
	v_lshl_add_u64 v[78:79], s[0:1], 0, v[2:3]
	v_readlane_b32 s0, v252, 20
	v_readlane_b32 s1, v252, 21
	s_cmp_lg_u64 s[22:23], 0
	v_add_u32_e32 v113, v4, v6
	v_lshl_add_u64 v[82:83], s[0:1], 0, v[2:3]
	v_readlane_b32 s0, v252, 16
	v_readlane_b32 s1, v252, 17
	s_mov_b32 s3, 0
	v_lshl_add_u64 v[68:69], s[62:63], 0, v[66:67]
	v_lshl_add_u64 v[88:89], s[0:1], 0, v[2:3]
	v_readlane_b32 s0, v252, 14
	v_readlane_b32 s1, v252, 15
	v_lshl_add_u64 v[70:71], s[6:7], 0, v[2:3]
	v_or_b32_e32 v105, 8, v1
	v_lshl_add_u64 v[92:93], s[0:1], 0, v[2:3]
	v_readlane_b32 s0, v252, 10
	v_readlane_b32 s1, v252, 11
	v_or_b32_e32 v107, 16, v1
	v_or_b32_e32 v109, 24, v1
	v_lshl_add_u64 v[72:73], s[60:61], 0, v[66:67]
	v_lshl_add_u64 v[76:77], s[56:57], 0, v[66:67]
	v_lshl_add_u64 v[80:81], s[54:55], 0, v[66:67]
	s_cselect_b64 s[14:15], -1, 0
	v_lshl_add_u64 v[84:85], s[52:53], 0, v[66:67]
	v_lshl_add_u64 v[86:87], s[20:21], 0, v[66:67]
	v_lshl_add_u64 v[90:91], s[18:19], 0, v[66:67]
	v_lshl_add_u64 v[94:95], s[16:17], 0, v[66:67]
	v_lshl_add_u64 v[96:97], s[70:71], 0, v[2:3]
	v_lshl_add_u64 v[98:99], s[12:13], 0, v[66:67]
	v_lshl_add_u64 v[100:101], s[0:1], 0, v[2:3]
	s_lshl_b32 s5, s4, 6
	s_lshl_b32 s6, s4, 2
	s_mov_b64 s[12:13], 0x80
	v_add_u32_e32 v115, 0x420, v113
	v_add_u32_e32 v117, 0x428, v113
	v_add_u32_e32 v118, 0x840, v113
	v_add_u32_e32 v119, 0x848, v113
	v_add_u32_e32 v120, 0x1080, v103
	v_add_u32_e32 v121, 0x1088, v103
	v_add_u32_e32 v122, 0x14a0, v103
	s_movk_i32 s7, 0x7fff
	s_mov_b32 s8, 0xffff0000
	v_mov_b32_e32 v123, 0x200
	v_add_u32_e32 v124, 0x14a8, v103
	v_add_u32_e32 v125, 0x18c0, v103
	s_branch .LBB0_836

; __global__ void __launch_bounds__(NWAVES * 64, 2) mega_fwd(Args args) {
;     ...
;                 p0_transpose_item(args.in[29], PLE, DM, Wpp, nullptr, 0, scr, r, lane); }
;             __syncthreads(); }
.LBB0_916:
	s_waitcnt vmcnt(0)
	s_barrier
	s_and_saveexec_b64 s[0:1], s[74:75]
	s_cbranch_execz .Lconv_arr_done
	buffer_wbl2 sc1
	s_waitcnt vmcnt(0)
	v_readlane_b32 s2, v252, 26
	v_readlane_b32 s3, v252, 27
	v_mov_b32_e32 v1, 0xac00
	v_mov_b32_e32 v2, 1
	s_nop 4
	global_atomic_add v1, v2, s[2:3]

; #define SEAM(k) do { if (IN(k) && IN((k) + 1)) xcd_barrier(bar); } while (0)
; __global__ void __launch_bounds__(NWAVES * 64, 2) mega_fwd(Args args) {
;     ...
;     if (IN(7)) { pg8::Gemm g{ZB, Wglu, M, 512, 512, 512, 512, 0, 0, 1}; pg8::StaticOrder S; S.init(M, 512, 1, G, bx);
;         pg8::EpiGlu E{ZB, args.in[19], Z2B}; pg8::gemm_phase<pg8::EpiGlu, true>(lds, g, S, E); }
;     SEAM(7);
.LBB0_1033:
	s_waitcnt vmcnt(0)
	s_barrier
	s_addk_i32 s88, 0x80
	s_and_saveexec_b64 s[6:7], s[74:75]
	s_cbranch_execz .Lz_arr_done
	s_and_b32 s10, s88, 7
	s_lshl_b32 s10, s10, 3
	s_bfe_u32 s11, s88, 0x30003
	s_or_b32 s10, s10, s11
	s_lshl_b32 s10, s10, 6
	s_add_i32 s10, s10, 0xfd0d020
	v_mov_b32_e32 v1, s10
	v_mov_b32_e32 v2, 1
	global_atomic_add v1, v2, s[66:67]

; #define SEAM(k) do { if (IN(k) && IN((k) + 1)) xcd_barrier(bar); } while (0)
; __global__ void __launch_bounds__(NWAVES * 64, 2) mega_fwd(Args args) {
;     ...
;     SEAM(7);
;     if (IN(8)) { pg8::StaticOrder S; S.init(M, DM, 1, G, bx);
;         { pg8::Gemm g{QB_, Wab, M, DM, 512, 512, 512, 0, 0, 1}; pg8::EpiBranch<false> E{(const unsigned char*)GATES, 0, MG}; pg8::gemm_phase<pg8::EpiBranch<false>, true>(lds, g, S, E); }
;         { pg8::Gemm g{Z2B, Wsb, M, DM, 512, 512, 512, 0, 0, 1}; pg8::EpiBranch<true> E{(const unsigned char*)GATES, 1024, MG}; pg8::gemm_phase<pg8::EpiBranch<true>, true>(lds, g, S, E); } }
.LBB0_1034:
	s_cmp_gt_i32 s85, 8
	s_cselect_b64 s[2:3], -1, 0
	s_and_b64 s[4:5], s[4:5], s[2:3]
	s_andn2_b64 vcc, exec, s[4:5]
	s_cbranch_vccnz .LBB0_1088
	s_waitcnt vmcnt(0)
	s_waitcnt vmcnt(0) lgkmcnt(0)
	s_barrier
	s_and_saveexec_b64 s[4:5], s[74:75]
	s_cbranch_execz .LBB0_1087
	s_and_b32 s6, s88, 7
	s_lshl_b32 s6, s6, 3
	s_bfe_u32 s7, s88, 0x30003
	s_or_b32 s6, s6, s7
	s_lshl_b32 s6, s6, 6
	s_add_i32 s6, s6, 0xfd0d000
	v_mov_b32_e32 v1, s6
	v_mov_b32_e32 v2, 0xfd0ec00
	v_mov_b32_e32 v3, 0xfd08000
	s_mov_b32 s8, 0
.Ldf7_spin:
	global_load_dword v4, v1, s[66:67] sc1
	global_load_dword v5, v1, s[66:67] offset:32 sc1
	global_load_dword v6, v2, s[66:67] sc1
	global_load_dword v16, v3, s[66:67] sc1
	s_waitcnt vmcnt(0)
	v_readfirstlane_b32 s9, v4
	v_readfirstlane_b32 s10, v5
	v_readfirstlane_b32 s11, v6
	v_readfirstlane_b32 s12, v16
	s_nop 3
	s_cmp_ge_u32 s9, 8
	s_cselect_b32 s9, 1, 0
	s_cmp_ge_u32 s10, 2
	s_cselect_b32 s10, 1, 0
	s_cmp_ge_u32 s11, 64
	s_cselect_b32 s11, 1, 0
	s_cmp_ge_u32 s12, 0xc0
	s_cselect_b32 s12, 1, 0
	s_and_b32 s9, s9, s10
	s_and_b32 s11, s11, s12
	s_and_b32 s9, s9, s11
	s_cmp_lg_u32 s9, 0
	s_cbranch_scc1 .Ldf7_ok
	s_sleep 1
	s_add_i32 s8, s8, 1
	s_cmp_lt_u32 s8, 0x20000
	s_cbranch_scc1 .Ldf7_spin
